# v93 + attention softmax: 32 v_sub(score - rowmax) per tile replaced by 16 packed v_pk_add into free registers (bit-identical)
# baseline (speedup 1.0000x reference)
.LBB0_789:
	v_add_u32_e32 v201, 0x3000, v197
	ds_read2_b64 v[202:205], v201 offset0:128 offset1:130
	v_mov_b32_e32 v222, v199
	v_pk_add_f32 v[224:225], v[36:37], v[222:223] op_sel_hi:[1,0] neg_lo:[0,1] neg_hi:[0,1]
	v_pk_add_f32 v[226:227], v[38:39], v[222:223] op_sel_hi:[1,0] neg_lo:[0,1] neg_hi:[0,1]
	v_pk_add_f32 v[228:229], v[40:41], v[222:223] op_sel_hi:[1,0] neg_lo:[0,1] neg_hi:[0,1]
	v_pk_add_f32 v[230:231], v[42:43], v[222:223] op_sel_hi:[1,0] neg_lo:[0,1] neg_hi:[0,1]
	v_pk_add_f32 v[232:233], v[44:45], v[222:223] op_sel_hi:[1,0] neg_lo:[0,1] neg_hi:[0,1]
	v_pk_add_f32 v[234:235], v[46:47], v[222:223] op_sel_hi:[1,0] neg_lo:[0,1] neg_hi:[0,1]
	v_pk_add_f32 v[236:237], v[48:49], v[222:223] op_sel_hi:[1,0] neg_lo:[0,1] neg_hi:[0,1]
	v_pk_add_f32 v[238:239], v[50:51], v[222:223] op_sel_hi:[1,0] neg_lo:[0,1] neg_hi:[0,1]
	v_pk_add_f32 v[240:241], v[52:53], v[222:223] op_sel_hi:[1,0] neg_lo:[0,1] neg_hi:[0,1]
	v_pk_add_f32 v[242:243], v[54:55], v[222:223] op_sel_hi:[1,0] neg_lo:[0,1] neg_hi:[0,1]
	v_pk_add_f32 v[244:245], v[56:57], v[222:223] op_sel_hi:[1,0] neg_lo:[0,1] neg_hi:[0,1]
	v_pk_add_f32 v[246:247], v[58:59], v[222:223] op_sel_hi:[1,0] neg_lo:[0,1] neg_hi:[0,1]
	v_pk_add_f32 v[248:249], v[60:61], v[222:223] op_sel_hi:[1,0] neg_lo:[0,1] neg_hi:[0,1]
	v_pk_add_f32 v[250:251], v[62:63], v[222:223] op_sel_hi:[1,0] neg_lo:[0,1] neg_hi:[0,1]
	v_pk_add_f32 v[252:253], v[64:65], v[222:223] op_sel_hi:[1,0] neg_lo:[0,1] neg_hi:[0,1]
	v_pk_add_f32 v[254:255], v[66:67], v[222:223] op_sel_hi:[1,0] neg_lo:[0,1] neg_hi:[0,1]
	v_exp_f32_e32 v198, v224
	v_exp_f32_e32 v53, v225
	v_exp_f32_e32 v54, v226
	v_exp_f32_e32 v55, v227
	v_exp_f32_e32 v56, v228
	v_exp_f32_e32 v57, v229
	v_exp_f32_e32 v58, v230
	v_add_u32_e32 v214, 0x4000, v197
	v_exp_f32_e32 v52, v240
	v_exp_f32_e32 v36, v241
	v_exp_f32_e32 v37, v242
	v_exp_f32_e32 v38, v243
	v_exp_f32_e32 v39, v244
	v_exp_f32_e32 v40, v245
	v_exp_f32_e32 v41, v246
	v_exp_f32_e32 v42, v247
	v_cvt_pk_bf16_f32 v206, v52, v36
	v_cvt_pk_bf16_f32 v207, v37, v38
	v_cvt_pk_bf16_f32 v208, v39, v40
	v_cvt_pk_bf16_f32 v209, v41, v42
	ds_read2_b64 v[210:213], v214 offset0:160 offset1:162
	s_waitcnt lgkmcnt(1)
	v_mfma_f32_32x32x16_bf16 v[20:35], v[202:205], v[206:209], v[20:35]
	ds_read2_b64 v[202:205], v201 offset0:132 offset1:134
	v_exp_f32_e32 v43, v248
	v_exp_f32_e32 v59, v249
	v_exp_f32_e32 v60, v250
	v_exp_f32_e32 v61, v251
	v_exp_f32_e32 v62, v252
	v_exp_f32_e32 v63, v253
	v_exp_f32_e32 v64, v254
	s_waitcnt lgkmcnt(1)
	v_mfma_f32_32x32x16_bf16 v[4:19], v[210:213], v[206:209], v[4:19]
	v_exp_f32_e32 v65, v255
	v_cvt_pk_bf16_f32 v206, v43, v59
	v_cvt_pk_bf16_f32 v207, v60, v61
	v_cvt_pk_bf16_f32 v208, v62, v63
	v_cvt_pk_bf16_f32 v209, v64, v65
	ds_read2_b64 v[210:213], v214 offset0:164 offset1:166
	v_exp_f32_e32 v66, v231
	s_waitcnt lgkmcnt(1)
	v_mfma_f32_32x32x16_bf16 v[20:35], v[202:205], v[206:209], v[20:35]
	ds_read2_b64 v[202:205], v201 offset0:136 offset1:138
	s_waitcnt lgkmcnt(1)
	v_mfma_f32_32x32x16_bf16 v[4:19], v[210:213], v[206:209], v[4:19]
	v_cvt_pk_bf16_f32 v206, v198, v53
	v_cvt_pk_bf16_f32 v207, v54, v55
	v_cvt_pk_bf16_f32 v208, v56, v57
	v_cvt_pk_bf16_f32 v209, v58, v66
	ds_read2_b64 v[210:213], v214 offset0:168 offset1:170
	s_waitcnt lgkmcnt(1)
	v_mfma_f32_32x32x16_bf16 v[20:35], v[202:205], v[206:209], v[20:35]
	ds_read2_b64 v[202:205], v201 offset0:140 offset1:142
	v_exp_f32_e32 v44, v232
	v_exp_f32_e32 v45, v233
	v_exp_f32_e32 v46, v234
	v_exp_f32_e32 v47, v235
	v_exp_f32_e32 v48, v236
	v_exp_f32_e32 v49, v237
	s_waitcnt lgkmcnt(1)
	v_mfma_f32_32x32x16_bf16 v[4:19], v[210:213], v[206:209], v[4:19]
	v_exp_f32_e32 v50, v238
	v_exp_f32_e32 v51, v239
	v_cvt_pk_bf16_f32 v206, v44, v45
	v_cvt_pk_bf16_f32 v207, v46, v47
	v_cvt_pk_bf16_f32 v208, v48, v49
	v_cvt_pk_bf16_f32 v209, v50, v51
	s_add_i32 s62, s8, -5
	s_waitcnt lgkmcnt(0)
	v_mfma_f32_32x32x16_bf16 v[20:35], v[202:205], v[206:209], v[20:35]
	ds_read2_b64 v[202:205], v214 offset0:172 offset1:174
	v_cmp_lt_u32_e32 vcc, s62, v194
	s_waitcnt lgkmcnt(0)
	v_mfma_f32_32x32x16_bf16 v[4:19], v[202:205], v[206:209], v[4:19]
	s_and_saveexec_b64 s[6:7], vcc
	s_cbranch_execz .LBB0_791
	v_add3_u32 v67, v161, v190, s79
	s_waitcnt vmcnt(6)
	ds_write_b128 v187, v[128:131] offset:22016
	ds_write_b128 v188, v[112:115] offset:22016
	ds_write_b128 v189, v[116:119] offset:22016
	ds_write2_b64 v67, v[124:125], v[126:127] offset1:1
	v_add3_u32 v67, v161, v192, s79
	ds_write2_b64 v67, v[120:121], v[122:123] offset1:1

.LBB0_794:
	v_mov_b32_e32 v222, v171
	v_pk_add_f32 v[224:225], v[36:37], v[222:223] op_sel_hi:[1,0] neg_lo:[0,1] neg_hi:[0,1]
	v_pk_add_f32 v[226:227], v[38:39], v[222:223] op_sel_hi:[1,0] neg_lo:[0,1] neg_hi:[0,1]
	v_pk_add_f32 v[228:229], v[40:41], v[222:223] op_sel_hi:[1,0] neg_lo:[0,1] neg_hi:[0,1]
	v_pk_add_f32 v[230:231], v[42:43], v[222:223] op_sel_hi:[1,0] neg_lo:[0,1] neg_hi:[0,1]
	v_pk_add_f32 v[232:233], v[44:45], v[222:223] op_sel_hi:[1,0] neg_lo:[0,1] neg_hi:[0,1]
	v_pk_add_f32 v[234:235], v[46:47], v[222:223] op_sel_hi:[1,0] neg_lo:[0,1] neg_hi:[0,1]
	v_pk_add_f32 v[236:237], v[48:49], v[222:223] op_sel_hi:[1,0] neg_lo:[0,1] neg_hi:[0,1]
	v_pk_add_f32 v[238:239], v[50:51], v[222:223] op_sel_hi:[1,0] neg_lo:[0,1] neg_hi:[0,1]
	v_pk_add_f32 v[240:241], v[52:53], v[222:223] op_sel_hi:[1,0] neg_lo:[0,1] neg_hi:[0,1]
	v_pk_add_f32 v[242:243], v[54:55], v[222:223] op_sel_hi:[1,0] neg_lo:[0,1] neg_hi:[0,1]
	v_pk_add_f32 v[244:245], v[56:57], v[222:223] op_sel_hi:[1,0] neg_lo:[0,1] neg_hi:[0,1]
	v_pk_add_f32 v[246:247], v[58:59], v[222:223] op_sel_hi:[1,0] neg_lo:[0,1] neg_hi:[0,1]
	v_pk_add_f32 v[248:249], v[60:61], v[222:223] op_sel_hi:[1,0] neg_lo:[0,1] neg_hi:[0,1]
	v_pk_add_f32 v[250:251], v[62:63], v[222:223] op_sel_hi:[1,0] neg_lo:[0,1] neg_hi:[0,1]
	v_pk_add_f32 v[252:253], v[64:65], v[222:223] op_sel_hi:[1,0] neg_lo:[0,1] neg_hi:[0,1]
	v_pk_add_f32 v[254:255], v[66:67], v[222:223] op_sel_hi:[1,0] neg_lo:[0,1] neg_hi:[0,1]
	v_exp_f32_e32 v201, v226
	v_exp_f32_e32 v55, v243
	v_exp_f32_e32 v202, v227
	v_exp_f32_e32 v199, v224
	v_exp_f32_e32 v56, v244
	v_exp_f32_e32 v52, v240
	v_exp_f32_e32 v53, v241
	v_exp_f32_e32 v203, v228
	v_exp_f32_e32 v200, v225
	v_exp_f32_e32 v57, v245
	v_exp_f32_e32 v54, v242
	v_exp_f32_e32 v204, v229
	v_exp_f32_e32 v58, v246
	v_add_f32_e32 v36, v52, v199
	v_exp_f32_e32 v205, v230
	v_add_f32_e32 v36, 0, v36
	v_add_f32_e32 v37, v53, v200
	v_exp_f32_e32 v59, v247
	v_add_f32_e32 v36, v37, v36
	v_add_f32_e32 v37, v54, v201
	v_exp_f32_e32 v206, v231
	v_add_f32_e32 v36, v37, v36
	v_add_f32_e32 v37, v55, v202
	v_exp_f32_e32 v60, v248
	v_add_f32_e32 v36, v37, v36
	v_add_f32_e32 v37, v56, v203
	v_exp_f32_e32 v207, v232
	v_add_f32_e32 v36, v37, v36
	v_add_f32_e32 v37, v57, v204
	v_add_f32_e32 v36, v37, v36
	v_add_f32_e32 v37, v58, v205
	v_add_f32_e32 v36, v37, v36
	v_add_f32_e32 v37, v59, v206
	v_add_f32_e32 v36, v37, v36
	v_add_f32_e32 v37, v60, v207
	v_add_f32_e32 v209, v37, v36
	v_exp_f32_e32 v61, v249
	v_exp_f32_e32 v62, v250
	v_add_u32_e32 v63, 0x8800, v197
	v_exp_f32_e32 v208, v233
	v_exp_f32_e32 v211, v234
	ds_read2_b64 v[36:39], v63 offset0:64 offset1:66
	v_exp_f32_e32 v212, v251
	v_cvt_pk_bf16_f32 v40, v52, v53
	v_add_u32_e32 v52, 0x9800, v197
	ds_read2_b64 v[44:47], v52 offset0:96 offset1:98
	v_cvt_pk_bf16_f32 v41, v54, v55
	v_cvt_pk_bf16_f32 v42, v56, v57
	v_cvt_pk_bf16_f32 v43, v58, v59
	v_exp_f32_e32 v57, v235
	s_waitcnt lgkmcnt(1)
	v_mfma_f32_32x32x16_bf16 v[20:35], v[36:39], v[40:43], v[20:35]
	v_exp_f32_e32 v53, v252
	v_exp_f32_e32 v54, v253
	v_exp_f32_e32 v55, v254
	ds_read2_b64 v[36:39], v63 offset0:68 offset1:70
	s_waitcnt lgkmcnt(1)
	v_mfma_f32_32x32x16_bf16 v[4:19], v[44:47], v[40:43], v[4:19]
	ds_read2_b64 v[44:47], v52 offset0:100 offset1:102
	v_add_f32_e32 v210, v61, v208
	v_exp_f32_e32 v56, v255
	v_cvt_pk_bf16_f32 v40, v60, v61
	v_cvt_pk_bf16_f32 v41, v62, v212
	v_cvt_pk_bf16_f32 v42, v53, v54
	v_cvt_pk_bf16_f32 v43, v55, v56
	s_waitcnt lgkmcnt(1)
	v_mfma_f32_32x32x16_bf16 v[20:35], v[36:39], v[40:43], v[20:35]
	v_add_f32_e32 v36, v210, v209
	v_add_f32_e32 v37, v62, v211
	v_add_f32_e32 v36, v37, v36
	v_add_f32_e32 v37, v212, v57
	v_add_f32_e32 v58, v37, v36
	ds_read2_b64 v[36:39], v63 offset0:72 offset1:74
	s_waitcnt lgkmcnt(1)
	v_mfma_f32_32x32x16_bf16 v[4:19], v[44:47], v[40:43], v[4:19]
	ds_read2_b64 v[44:47], v52 offset0:104 offset1:106
	v_exp_f32_e32 v48, v236
	v_cvt_pk_bf16_f32 v40, v199, v200
	v_cvt_pk_bf16_f32 v41, v201, v202
	v_cvt_pk_bf16_f32 v42, v203, v204
	v_cvt_pk_bf16_f32 v43, v205, v206
	v_mov_b32_e32 v199, v171
	s_waitcnt lgkmcnt(1)
	v_mfma_f32_32x32x16_bf16 v[20:35], v[36:39], v[40:43], v[20:35]
	v_add_f32_e32 v36, v53, v48
	v_add_f32_e32 v53, v36, v58
	v_exp_f32_e32 v49, v237
	v_exp_f32_e32 v50, v238
	ds_read2_b64 v[36:39], v63 offset0:76 offset1:78
	s_waitcnt lgkmcnt(1)
	v_mfma_f32_32x32x16_bf16 v[4:19], v[44:47], v[40:43], v[4:19]
	ds_read2_b64 v[44:47], v52 offset0:108 offset1:110
	v_exp_f32_e32 v51, v239
	v_cvt_pk_bf16_f32 v40, v207, v208
	v_cvt_pk_bf16_f32 v41, v211, v57
	v_cvt_pk_bf16_f32 v42, v48, v49
	v_cvt_pk_bf16_f32 v43, v50, v51
	s_waitcnt lgkmcnt(1)
	v_mfma_f32_32x32x16_bf16 v[20:35], v[36:39], v[40:43], v[20:35]
	v_add_f32_e32 v36, v54, v49
	v_add_f32_e32 v36, v36, v53
	v_add_f32_e32 v37, v55, v50
	v_add_f32_e32 v36, v37, v36
	v_add_f32_e32 v37, v56, v51
	v_add_f32_e32 v36, v37, v36
	v_fmac_f32_e32 v36, v198, v172
	s_waitcnt lgkmcnt(0)
	v_mfma_f32_32x32x16_bf16 v[4:19], v[44:47], v[40:43], v[4:19]
	v_mov_b32_e32 v198, v36

.LBB0_800:
	v_mov_b32_e32 v222, v170
	v_pk_add_f32 v[224:225], v[36:37], v[222:223] op_sel_hi:[1,0] neg_lo:[0,1] neg_hi:[0,1]
	v_pk_add_f32 v[226:227], v[38:39], v[222:223] op_sel_hi:[1,0] neg_lo:[0,1] neg_hi:[0,1]
	v_pk_add_f32 v[228:229], v[40:41], v[222:223] op_sel_hi:[1,0] neg_lo:[0,1] neg_hi:[0,1]
	v_pk_add_f32 v[230:231], v[42:43], v[222:223] op_sel_hi:[1,0] neg_lo:[0,1] neg_hi:[0,1]
	v_pk_add_f32 v[232:233], v[44:45], v[222:223] op_sel_hi:[1,0] neg_lo:[0,1] neg_hi:[0,1]
	v_pk_add_f32 v[234:235], v[46:47], v[222:223] op_sel_hi:[1,0] neg_lo:[0,1] neg_hi:[0,1]
	v_pk_add_f32 v[236:237], v[48:49], v[222:223] op_sel_hi:[1,0] neg_lo:[0,1] neg_hi:[0,1]
	v_pk_add_f32 v[238:239], v[50:51], v[222:223] op_sel_hi:[1,0] neg_lo:[0,1] neg_hi:[0,1]
	v_pk_add_f32 v[240:241], v[52:53], v[222:223] op_sel_hi:[1,0] neg_lo:[0,1] neg_hi:[0,1]
	v_pk_add_f32 v[242:243], v[54:55], v[222:223] op_sel_hi:[1,0] neg_lo:[0,1] neg_hi:[0,1]
	v_pk_add_f32 v[244:245], v[56:57], v[222:223] op_sel_hi:[1,0] neg_lo:[0,1] neg_hi:[0,1]
	v_pk_add_f32 v[246:247], v[58:59], v[222:223] op_sel_hi:[1,0] neg_lo:[0,1] neg_hi:[0,1]
	v_pk_add_f32 v[248:249], v[60:61], v[222:223] op_sel_hi:[1,0] neg_lo:[0,1] neg_hi:[0,1]
	v_pk_add_f32 v[250:251], v[62:63], v[222:223] op_sel_hi:[1,0] neg_lo:[0,1] neg_hi:[0,1]
	v_pk_add_f32 v[252:253], v[64:65], v[222:223] op_sel_hi:[1,0] neg_lo:[0,1] neg_hi:[0,1]
	v_pk_add_f32 v[254:255], v[66:67], v[222:223] op_sel_hi:[1,0] neg_lo:[0,1] neg_hi:[0,1]
	v_exp_f32_e32 v199, v226
	v_exp_f32_e32 v55, v243
	v_exp_f32_e32 v200, v227
	v_exp_f32_e32 v171, v224
	v_exp_f32_e32 v56, v244
	v_exp_f32_e32 v52, v240
	v_exp_f32_e32 v53, v241
	v_exp_f32_e32 v201, v228
	v_exp_f32_e32 v172, v225
	v_exp_f32_e32 v57, v245
	v_exp_f32_e32 v54, v242
	v_exp_f32_e32 v202, v229
	v_exp_f32_e32 v58, v246
	v_add_f32_e32 v36, v52, v171
	v_exp_f32_e32 v203, v230
	v_add_f32_e32 v36, 0, v36
	v_add_f32_e32 v37, v53, v172
	v_exp_f32_e32 v59, v247
	v_add_f32_e32 v36, v37, v36
	v_add_f32_e32 v37, v54, v199
	v_exp_f32_e32 v204, v231
	v_add_f32_e32 v36, v37, v36
	v_add_f32_e32 v37, v55, v200
	v_exp_f32_e32 v60, v248
	v_add_f32_e32 v36, v37, v36
	v_add_f32_e32 v37, v56, v201
	v_exp_f32_e32 v205, v232
	v_add_f32_e32 v36, v37, v36
	v_add_f32_e32 v37, v57, v202
	v_add_f32_e32 v36, v37, v36
	v_add_f32_e32 v37, v58, v203
	v_add_f32_e32 v36, v37, v36
	v_add_f32_e32 v37, v59, v204
	v_add_f32_e32 v36, v37, v36
	v_add_f32_e32 v37, v60, v205
	v_add_f32_e32 v207, v37, v36
	v_exp_f32_e32 v61, v249
	v_exp_f32_e32 v62, v250
	v_add_u32_e32 v63, 0xe000, v197
	v_exp_f32_e32 v206, v233
	v_exp_f32_e32 v209, v234
	ds_read2_b64 v[36:39], v63 offset1:2
	v_exp_f32_e32 v210, v251
	v_cvt_pk_bf16_f32 v40, v52, v53
	v_add_u32_e32 v52, 0xf000, v197
	ds_read2_b64 v[44:47], v52 offset0:32 offset1:34
	v_cvt_pk_bf16_f32 v41, v54, v55
	v_cvt_pk_bf16_f32 v42, v56, v57
	v_cvt_pk_bf16_f32 v43, v58, v59
	v_exp_f32_e32 v57, v235
	s_waitcnt lgkmcnt(1)
	v_mfma_f32_32x32x16_bf16 v[20:35], v[36:39], v[40:43], v[20:35]
	v_exp_f32_e32 v53, v252
	v_exp_f32_e32 v54, v253
	v_exp_f32_e32 v55, v254
	ds_read2_b64 v[36:39], v63 offset0:4 offset1:6
	s_waitcnt lgkmcnt(1)
	v_mfma_f32_32x32x16_bf16 v[4:19], v[44:47], v[40:43], v[4:19]
	ds_read2_b64 v[44:47], v52 offset0:36 offset1:38
	v_add_f32_e32 v208, v61, v206
	v_exp_f32_e32 v56, v255
	v_cvt_pk_bf16_f32 v40, v60, v61
	v_cvt_pk_bf16_f32 v41, v62, v210
	v_cvt_pk_bf16_f32 v42, v53, v54
	v_cvt_pk_bf16_f32 v43, v55, v56
	s_waitcnt lgkmcnt(1)
	v_mfma_f32_32x32x16_bf16 v[20:35], v[36:39], v[40:43], v[20:35]
	v_add_f32_e32 v36, v208, v207
	v_add_f32_e32 v37, v62, v209
	v_add_f32_e32 v36, v37, v36
	v_add_f32_e32 v37, v210, v57
	v_add_f32_e32 v58, v37, v36
	ds_read2_b64 v[36:39], v63 offset0:8 offset1:10
	s_waitcnt lgkmcnt(1)
	v_mfma_f32_32x32x16_bf16 v[4:19], v[44:47], v[40:43], v[4:19]
	ds_read2_b64 v[44:47], v52 offset0:40 offset1:42
	v_exp_f32_e32 v48, v236
	v_cvt_pk_bf16_f32 v40, v171, v172
	v_cvt_pk_bf16_f32 v41, v199, v200
	v_cvt_pk_bf16_f32 v42, v201, v202
	v_cvt_pk_bf16_f32 v43, v203, v204
	v_mov_b32_e32 v199, v170
	s_waitcnt lgkmcnt(1)
	v_mfma_f32_32x32x16_bf16 v[20:35], v[36:39], v[40:43], v[20:35]
	v_add_f32_e32 v36, v53, v48
	v_add_f32_e32 v53, v36, v58
	v_exp_f32_e32 v49, v237
	v_exp_f32_e32 v50, v238
	ds_read2_b64 v[36:39], v63 offset0:12 offset1:14
	s_waitcnt lgkmcnt(1)
	v_mfma_f32_32x32x16_bf16 v[4:19], v[44:47], v[40:43], v[4:19]
	ds_read2_b64 v[44:47], v52 offset0:44 offset1:46
	v_exp_f32_e32 v51, v239
	v_cvt_pk_bf16_f32 v40, v205, v206
	v_cvt_pk_bf16_f32 v41, v209, v57
	v_cvt_pk_bf16_f32 v42, v48, v49
	v_cvt_pk_bf16_f32 v43, v50, v51
	s_waitcnt lgkmcnt(1)
	v_mfma_f32_32x32x16_bf16 v[20:35], v[36:39], v[40:43], v[20:35]
	v_add_f32_e32 v36, v54, v49
	v_add_f32_e32 v36, v36, v53
	v_add_f32_e32 v37, v55, v50
	v_add_f32_e32 v36, v37, v36
	v_add_f32_e32 v37, v56, v51
	v_add_f32_e32 v36, v37, v36
	v_fmac_f32_e32 v36, v198, v2
	s_waitcnt lgkmcnt(0)
	v_mfma_f32_32x32x16_bf16 v[4:19], v[44:47], v[40:43], v[4:19]
	v_mov_b32_e32 v198, v36

.LBB0_2032:
	v_add_u32_e32 v201, 0x3000, v197
	ds_read2_b64 v[202:205], v201 offset0:128 offset1:130
	v_mov_b32_e32 v222, v199
	v_pk_add_f32 v[224:225], v[36:37], v[222:223] op_sel_hi:[1,0] neg_lo:[0,1] neg_hi:[0,1]
	v_pk_add_f32 v[226:227], v[38:39], v[222:223] op_sel_hi:[1,0] neg_lo:[0,1] neg_hi:[0,1]
	v_pk_add_f32 v[228:229], v[40:41], v[222:223] op_sel_hi:[1,0] neg_lo:[0,1] neg_hi:[0,1]
	v_pk_add_f32 v[230:231], v[42:43], v[222:223] op_sel_hi:[1,0] neg_lo:[0,1] neg_hi:[0,1]
	v_pk_add_f32 v[232:233], v[44:45], v[222:223] op_sel_hi:[1,0] neg_lo:[0,1] neg_hi:[0,1]
	v_pk_add_f32 v[234:235], v[46:47], v[222:223] op_sel_hi:[1,0] neg_lo:[0,1] neg_hi:[0,1]
	v_pk_add_f32 v[236:237], v[48:49], v[222:223] op_sel_hi:[1,0] neg_lo:[0,1] neg_hi:[0,1]
	v_pk_add_f32 v[238:239], v[50:51], v[222:223] op_sel_hi:[1,0] neg_lo:[0,1] neg_hi:[0,1]
	v_pk_add_f32 v[240:241], v[52:53], v[222:223] op_sel_hi:[1,0] neg_lo:[0,1] neg_hi:[0,1]
	v_pk_add_f32 v[242:243], v[54:55], v[222:223] op_sel_hi:[1,0] neg_lo:[0,1] neg_hi:[0,1]
	v_pk_add_f32 v[244:245], v[56:57], v[222:223] op_sel_hi:[1,0] neg_lo:[0,1] neg_hi:[0,1]
	v_pk_add_f32 v[246:247], v[58:59], v[222:223] op_sel_hi:[1,0] neg_lo:[0,1] neg_hi:[0,1]
	v_pk_add_f32 v[248:249], v[60:61], v[222:223] op_sel_hi:[1,0] neg_lo:[0,1] neg_hi:[0,1]
	v_pk_add_f32 v[250:251], v[62:63], v[222:223] op_sel_hi:[1,0] neg_lo:[0,1] neg_hi:[0,1]
	v_pk_add_f32 v[252:253], v[64:65], v[222:223] op_sel_hi:[1,0] neg_lo:[0,1] neg_hi:[0,1]
	v_pk_add_f32 v[254:255], v[66:67], v[222:223] op_sel_hi:[1,0] neg_lo:[0,1] neg_hi:[0,1]
	v_exp_f32_e32 v198, v224
	v_exp_f32_e32 v53, v225
	v_exp_f32_e32 v54, v226
	v_exp_f32_e32 v55, v227
	v_exp_f32_e32 v56, v228
	v_exp_f32_e32 v57, v229
	v_exp_f32_e32 v58, v230
	v_add_u32_e32 v214, 0x4000, v197
	v_exp_f32_e32 v52, v240
	v_exp_f32_e32 v36, v241
	v_exp_f32_e32 v37, v242
	v_exp_f32_e32 v38, v243
	v_exp_f32_e32 v39, v244
	v_exp_f32_e32 v40, v245
	v_exp_f32_e32 v41, v246
	v_exp_f32_e32 v42, v247
	v_cvt_pk_bf16_f32 v206, v52, v36
	v_cvt_pk_bf16_f32 v207, v37, v38
	v_cvt_pk_bf16_f32 v208, v39, v40
	v_cvt_pk_bf16_f32 v209, v41, v42
	ds_read2_b64 v[210:213], v214 offset0:160 offset1:162
	s_waitcnt lgkmcnt(1)
	v_mfma_f32_32x32x16_bf16 v[20:35], v[202:205], v[206:209], v[20:35]
	ds_read2_b64 v[202:205], v201 offset0:132 offset1:134
	v_exp_f32_e32 v43, v248
	v_exp_f32_e32 v59, v249
	v_exp_f32_e32 v60, v250
	v_exp_f32_e32 v61, v251
	v_exp_f32_e32 v62, v252
	v_exp_f32_e32 v63, v253
	v_exp_f32_e32 v64, v254
	s_waitcnt lgkmcnt(1)
	v_mfma_f32_32x32x16_bf16 v[4:19], v[210:213], v[206:209], v[4:19]
	v_exp_f32_e32 v65, v255
	v_cvt_pk_bf16_f32 v206, v43, v59
	v_cvt_pk_bf16_f32 v207, v60, v61
	v_cvt_pk_bf16_f32 v208, v62, v63
	v_cvt_pk_bf16_f32 v209, v64, v65
	ds_read2_b64 v[210:213], v214 offset0:164 offset1:166
	v_exp_f32_e32 v66, v231
	s_waitcnt lgkmcnt(1)
	v_mfma_f32_32x32x16_bf16 v[20:35], v[202:205], v[206:209], v[20:35]
	ds_read2_b64 v[202:205], v201 offset0:136 offset1:138
	s_waitcnt lgkmcnt(1)
	v_mfma_f32_32x32x16_bf16 v[4:19], v[210:213], v[206:209], v[4:19]
	v_cvt_pk_bf16_f32 v206, v198, v53
	v_cvt_pk_bf16_f32 v207, v54, v55
	v_cvt_pk_bf16_f32 v208, v56, v57
	v_cvt_pk_bf16_f32 v209, v58, v66
	ds_read2_b64 v[210:213], v214 offset0:168 offset1:170
	s_waitcnt lgkmcnt(1)
	v_mfma_f32_32x32x16_bf16 v[20:35], v[202:205], v[206:209], v[20:35]
	ds_read2_b64 v[202:205], v201 offset0:140 offset1:142
	v_exp_f32_e32 v44, v232
	v_exp_f32_e32 v45, v233
	v_exp_f32_e32 v46, v234
	v_exp_f32_e32 v47, v235
	v_exp_f32_e32 v48, v236
	v_exp_f32_e32 v49, v237
	s_waitcnt lgkmcnt(1)
	v_mfma_f32_32x32x16_bf16 v[4:19], v[210:213], v[206:209], v[4:19]
	v_exp_f32_e32 v50, v238
	v_exp_f32_e32 v51, v239
	v_cvt_pk_bf16_f32 v206, v44, v45
	v_cvt_pk_bf16_f32 v207, v46, v47
	v_cvt_pk_bf16_f32 v208, v48, v49
	v_cvt_pk_bf16_f32 v209, v50, v51
	s_add_i32 s62, s8, -5
	s_waitcnt lgkmcnt(0)
	v_mfma_f32_32x32x16_bf16 v[20:35], v[202:205], v[206:209], v[20:35]
	ds_read2_b64 v[202:205], v214 offset0:172 offset1:174
	v_cmp_lt_u32_e32 vcc, s62, v194
	s_waitcnt lgkmcnt(0)
	v_mfma_f32_32x32x16_bf16 v[4:19], v[202:205], v[206:209], v[4:19]
	s_and_saveexec_b64 s[6:7], vcc
	s_cbranch_execz .LBB0_2034
	v_add3_u32 v67, v161, v190, s78
	s_waitcnt vmcnt(6)
	ds_write_b128 v187, v[128:131] offset:22016
	ds_write_b128 v188, v[112:115] offset:22016
	ds_write_b128 v189, v[116:119] offset:22016
	ds_write2_b64 v67, v[124:125], v[126:127] offset1:1
	v_add3_u32 v67, v161, v192, s78
	ds_write2_b64 v67, v[120:121], v[122:123] offset1:1
